# scan loop hand-scheduled (reads ahead, flush after staging) plus qkvb row-rms prepass with all loads in flight, no store drain before the tile barrier
# speedup vs baseline: 1.0055x; 1.0031x over previous
; #define LAS __attribute__((address_space(3)))
; #define EPI_DONE do { } while (0)
; DI void phase_qkvb(const P& p, char* shm) {
;     ...
;     for (int L = blockIdx.x; L < total; L += gridDim.x) {
;         const bool isq = L < nM * 6;
;         int pm, pn;
;         if (isq) tile_of(L, nM, 6, pm, pn); else tile_of(L - nM * 6, nM, 8, pm, pn);
;         const int brow = pm * 256;
;         if (isq) row_rms<512>((const bf16_t*)(p.ws + O_QLAT), brow, rs); else row_rms<256>((const bf16_t*)(p.ws + O_KVLAT), brow, rs);
;         const bf16_t* Aact = (const bf16_t*)(p.ws + (isq ? O_QLAT : O_KVLAT));
;         const bf16_t* Wt = (const bf16_t*)(p.ws + (isq ? O_WQB : O_WKVB));
;         const bool tr = !isq && pn >= 4;
;         gemm_tile(tr ? Wt : Aact, tr ? Aact : Wt, isq ? 512 : 256, tr ? pn * 256 : brow, tr ? brow : pn * 256, (LAS unsigned char*)shm, acc);
;         if (isq) {
;             if (pn < 4) {
;                 EPI_IDX
; #pragma unroll
;                 for (int ai = 0; ai < 2; ++ai)
; #pragma unroll
;                     for (int m = 0; m < 4; ++m) {
;                         const int lr = ai * 128 + wr * 64 + m * 16 + fr;
;                         const float s = rs[lr];
; #pragma unroll
;                         for (int bj = 0; bj < 2; ++bj)
; #pragma unroll
;                             for (int n = 0; n < 2; ++n) {
;                                 const f32x4 v = acc[ai][bj][m][n];
;                                 st4((bf16_t*)(p.ws + O_QM) + (size_t)(brow + lr) * 1536 + (pn * 2 + bj) * 192 + wc * 32 + n * 16 + fq * 4, v[0] * s, v[1] * s, v[2] * s, v[3] * s);
;                             }
;                     }
;                 EPI_DONE;
;             } else {
;                 epi_rope<64>(acc, p, brow, (bf16_t*)(p.ws + O_QM), 1536, (pn - 4) * 4 * 192 + 128, 192, rs, 4);
;             }
;         } else if (!tr) {
;             epi_plain(acc, brow, (bf16_t*)(p.ws + O_KN), 1024, pn * 256, rs);
;         } else {
;             epi_T<64>(acc, (pn - 4) * 256, brow, (bf16_t*)(p.ws + O_VMT), 1024, rs);
;         }
;         __syncthreads();
;     }
.LBB0_909:
	s_add_i32 s80, s80, s30
	s_cmpk_lt_i32 s80, 0x3b8
	s_barrier
	s_cbranch_scc0 .LBB0_1071

; DI float bf2f(unsigned short b) { return __uint_as_float(((unsigned)b) << 16); }
; DI int tidx() { int t = threadIdx.x; asm volatile("" : "+v"(t)); return t; }
; template <int W>
; DI void row_rms(const bf16_t* src, int row0, float* rs) {
;     const int tid = tidx(), r = tid >> 1, hf = tid & 1;
;     const bf16_t* q = src + (size_t)(row0 + r) * W + hf * (W / 2);
;     float ss = 0.f;
; #pragma unroll 4
;     for (int i = 0; i < W / 16; ++i) {
;         const bf16x8 v = *(const bf16x8*)(q + i * 8);
; #pragma unroll
;         for (int e = 0; e < 8; ++e) { const float f = bf2f((unsigned short)v[e]); ss += f * f; }
;     }
;     ss += __shfl_xor(ss, 1);
;     if (hf == 0) rs[r] = rsqrtf(ss * (1.f / W) + 1e-6f);
;     __syncthreads();
; }
.LBB0_916:
	global_load_dwordx4 v[6:9], v[0:1], off offset:-32
	global_load_dwordx4 v[10:13], v[0:1], off offset:-16
	global_load_dwordx4 v[14:17], v[0:1], off offset:0
	global_load_dwordx4 v[18:21], v[0:1], off offset:16
	global_load_dwordx4 v[22:25], v[0:1], off offset:32
	global_load_dwordx4 v[26:29], v[0:1], off offset:48
	global_load_dwordx4 v[30:33], v[0:1], off offset:64
	global_load_dwordx4 v[34:37], v[0:1], off offset:80
	global_load_dwordx4 v[38:41], v[0:1], off offset:96
	global_load_dwordx4 v[42:45], v[0:1], off offset:112
	global_load_dwordx4 v[46:49], v[0:1], off offset:128
	global_load_dwordx4 v[50:53], v[0:1], off offset:144
	global_load_dwordx4 v[54:57], v[0:1], off offset:160
	global_load_dwordx4 v[58:61], v[0:1], off offset:176
	global_load_dwordx4 v[62:65], v[0:1], off offset:192
	global_load_dwordx4 v[66:69], v[0:1], off offset:208
	global_load_dwordx4 v[70:73], v[0:1], off offset:224
	global_load_dwordx4 v[74:77], v[0:1], off offset:240
	global_load_dwordx4 v[78:81], v[0:1], off offset:256
	global_load_dwordx4 v[82:85], v[0:1], off offset:272
	global_load_dwordx4 v[86:89], v[0:1], off offset:288
	global_load_dwordx4 v[90:93], v[0:1], off offset:304
	global_load_dwordx4 v[94:97], v[0:1], off offset:320
	global_load_dwordx4 v[98:101], v[0:1], off offset:336
	global_load_dwordx4 v[102:105], v[0:1], off offset:352
	global_load_dwordx4 v[106:109], v[0:1], off offset:368
	global_load_dwordx4 v[110:113], v[0:1], off offset:384
	global_load_dwordx4 v[114:117], v[0:1], off offset:400
	global_load_dwordx4 v[118:121], v[0:1], off offset:416
	global_load_dwordx4 v[122:125], v[0:1], off offset:432
	global_load_dwordx4 v[126:129], v[0:1], off offset:448
	global_load_dwordx4 v[130:133], v[0:1], off offset:464
	s_waitcnt vmcnt(31)
	v_lshlrev_b32_e32 v5, 16, v6
	v_and_b32_e32 v6, 0xffff0000, v6
	v_fmac_f32_e32 v4, v5, v5
	v_fmac_f32_e32 v4, v6, v6
	v_lshlrev_b32_e32 v5, 16, v7
	v_and_b32_e32 v7, 0xffff0000, v7
	v_fmac_f32_e32 v4, v5, v5
	v_fmac_f32_e32 v4, v7, v7
	v_lshlrev_b32_e32 v5, 16, v8
	v_and_b32_e32 v8, 0xffff0000, v8
	v_fmac_f32_e32 v4, v5, v5
	v_fmac_f32_e32 v4, v8, v8
	v_lshlrev_b32_e32 v5, 16, v9
	v_and_b32_e32 v9, 0xffff0000, v9
	v_fmac_f32_e32 v4, v5, v5
	v_fmac_f32_e32 v4, v9, v9
	s_waitcnt vmcnt(30)
	v_lshlrev_b32_e32 v5, 16, v10
	v_and_b32_e32 v10, 0xffff0000, v10
	v_fmac_f32_e32 v4, v5, v5
	v_fmac_f32_e32 v4, v10, v10
	v_lshlrev_b32_e32 v5, 16, v11
	v_and_b32_e32 v11, 0xffff0000, v11
	v_fmac_f32_e32 v4, v5, v5
	v_fmac_f32_e32 v4, v11, v11
	v_lshlrev_b32_e32 v5, 16, v12
	v_and_b32_e32 v12, 0xffff0000, v12
	v_fmac_f32_e32 v4, v5, v5
	v_fmac_f32_e32 v4, v12, v12
	v_lshlrev_b32_e32 v5, 16, v13
	v_and_b32_e32 v13, 0xffff0000, v13
	v_fmac_f32_e32 v4, v5, v5
	v_fmac_f32_e32 v4, v13, v13
	s_waitcnt vmcnt(29)
	v_lshlrev_b32_e32 v5, 16, v14
	v_and_b32_e32 v14, 0xffff0000, v14
	v_fmac_f32_e32 v4, v5, v5
	v_fmac_f32_e32 v4, v14, v14
	v_lshlrev_b32_e32 v5, 16, v15
	v_and_b32_e32 v15, 0xffff0000, v15
	v_fmac_f32_e32 v4, v5, v5
	v_fmac_f32_e32 v4, v15, v15
	v_lshlrev_b32_e32 v5, 16, v16
	v_and_b32_e32 v16, 0xffff0000, v16
	v_fmac_f32_e32 v4, v5, v5
	v_fmac_f32_e32 v4, v16, v16
	v_lshlrev_b32_e32 v5, 16, v17
	v_and_b32_e32 v17, 0xffff0000, v17
	v_fmac_f32_e32 v4, v5, v5
	v_fmac_f32_e32 v4, v17, v17
	s_waitcnt vmcnt(28)
	v_lshlrev_b32_e32 v5, 16, v18
	v_and_b32_e32 v18, 0xffff0000, v18
	v_fmac_f32_e32 v4, v5, v5
	v_fmac_f32_e32 v4, v18, v18
	v_lshlrev_b32_e32 v5, 16, v19
	v_and_b32_e32 v19, 0xffff0000, v19
	v_fmac_f32_e32 v4, v5, v5
	v_fmac_f32_e32 v4, v19, v19
	v_lshlrev_b32_e32 v5, 16, v20
	v_and_b32_e32 v20, 0xffff0000, v20
	v_fmac_f32_e32 v4, v5, v5
	v_fmac_f32_e32 v4, v20, v20
	v_lshlrev_b32_e32 v5, 16, v21
	v_and_b32_e32 v21, 0xffff0000, v21
	v_fmac_f32_e32 v4, v5, v5
	v_fmac_f32_e32 v4, v21, v21
	s_waitcnt vmcnt(27)
	v_lshlrev_b32_e32 v5, 16, v22
	v_and_b32_e32 v22, 0xffff0000, v22
	v_fmac_f32_e32 v4, v5, v5
	v_fmac_f32_e32 v4, v22, v22
	v_lshlrev_b32_e32 v5, 16, v23
	v_and_b32_e32 v23, 0xffff0000, v23
	v_fmac_f32_e32 v4, v5, v5
	v_fmac_f32_e32 v4, v23, v23
	v_lshlrev_b32_e32 v5, 16, v24
	v_and_b32_e32 v24, 0xffff0000, v24
	v_fmac_f32_e32 v4, v5, v5
	v_fmac_f32_e32 v4, v24, v24
	v_lshlrev_b32_e32 v5, 16, v25
	v_and_b32_e32 v25, 0xffff0000, v25
	v_fmac_f32_e32 v4, v5, v5
	v_fmac_f32_e32 v4, v25, v25
	s_waitcnt vmcnt(26)
	v_lshlrev_b32_e32 v5, 16, v26
	v_and_b32_e32 v26, 0xffff0000, v26
	v_fmac_f32_e32 v4, v5, v5
	v_fmac_f32_e32 v4, v26, v26
	v_lshlrev_b32_e32 v5, 16, v27
	v_and_b32_e32 v27, 0xffff0000, v27
	v_fmac_f32_e32 v4, v5, v5
	v_fmac_f32_e32 v4, v27, v27
	v_lshlrev_b32_e32 v5, 16, v28
	v_and_b32_e32 v28, 0xffff0000, v28
	v_fmac_f32_e32 v4, v5, v5
	v_fmac_f32_e32 v4, v28, v28
	v_lshlrev_b32_e32 v5, 16, v29
	v_and_b32_e32 v29, 0xffff0000, v29
	v_fmac_f32_e32 v4, v5, v5
	v_fmac_f32_e32 v4, v29, v29
	s_waitcnt vmcnt(25)
	v_lshlrev_b32_e32 v5, 16, v30
	v_and_b32_e32 v30, 0xffff0000, v30
	v_fmac_f32_e32 v4, v5, v5
	v_fmac_f32_e32 v4, v30, v30
	v_lshlrev_b32_e32 v5, 16, v31
	v_and_b32_e32 v31, 0xffff0000, v31
	v_fmac_f32_e32 v4, v5, v5
	v_fmac_f32_e32 v4, v31, v31
	v_lshlrev_b32_e32 v5, 16, v32
	v_and_b32_e32 v32, 0xffff0000, v32
	v_fmac_f32_e32 v4, v5, v5
	v_fmac_f32_e32 v4, v32, v32
	v_lshlrev_b32_e32 v5, 16, v33
	v_and_b32_e32 v33, 0xffff0000, v33
	v_fmac_f32_e32 v4, v5, v5
	v_fmac_f32_e32 v4, v33, v33
	s_waitcnt vmcnt(24)
	v_lshlrev_b32_e32 v5, 16, v34
	v_and_b32_e32 v34, 0xffff0000, v34
	v_fmac_f32_e32 v4, v5, v5
	v_fmac_f32_e32 v4, v34, v34
	v_lshlrev_b32_e32 v5, 16, v35
	v_and_b32_e32 v35, 0xffff0000, v35
	v_fmac_f32_e32 v4, v5, v5
	v_fmac_f32_e32 v4, v35, v35
	v_lshlrev_b32_e32 v5, 16, v36
	v_and_b32_e32 v36, 0xffff0000, v36
	v_fmac_f32_e32 v4, v5, v5
	v_fmac_f32_e32 v4, v36, v36
	v_lshlrev_b32_e32 v5, 16, v37
	v_and_b32_e32 v37, 0xffff0000, v37
	v_fmac_f32_e32 v4, v5, v5
	v_fmac_f32_e32 v4, v37, v37
	s_waitcnt vmcnt(23)
; DI float bf2f(unsigned short b) { return __uint_as_float(((unsigned)b) << 16); }
; DI int tidx() { int t = threadIdx.x; asm volatile("" : "+v"(t)); return t; }
; template <int W>
; DI void row_rms(const bf16_t* src, int row0, float* rs) {
;     const int tid = tidx(), r = tid >> 1, hf = tid & 1;
;     const bf16_t* q = src + (size_t)(row0 + r) * W + hf * (W / 2);
;     float ss = 0.f;
; #pragma unroll 4
;     for (int i = 0; i < W / 16; ++i) {
;         const bf16x8 v = *(const bf16x8*)(q + i * 8);
; #pragma unroll
;         for (int e = 0; e < 8; ++e) { const float f = bf2f((unsigned short)v[e]); ss += f * f; }
;     }
;     ss += __shfl_xor(ss, 1);
;     if (hf == 0) rs[r] = rsqrtf(ss * (1.f / W) + 1e-6f);
;     __syncthreads();
; }
	v_lshlrev_b32_e32 v5, 16, v38
	v_and_b32_e32 v38, 0xffff0000, v38
	v_fmac_f32_e32 v4, v5, v5
	v_fmac_f32_e32 v4, v38, v38
	v_lshlrev_b32_e32 v5, 16, v39
	v_and_b32_e32 v39, 0xffff0000, v39
	v_fmac_f32_e32 v4, v5, v5
	v_fmac_f32_e32 v4, v39, v39
	v_lshlrev_b32_e32 v5, 16, v40
	v_and_b32_e32 v40, 0xffff0000, v40
	v_fmac_f32_e32 v4, v5, v5
	v_fmac_f32_e32 v4, v40, v40
	v_lshlrev_b32_e32 v5, 16, v41
	v_and_b32_e32 v41, 0xffff0000, v41
	v_fmac_f32_e32 v4, v5, v5
	v_fmac_f32_e32 v4, v41, v41
	s_waitcnt vmcnt(22)
	v_lshlrev_b32_e32 v5, 16, v42
	v_and_b32_e32 v42, 0xffff0000, v42
	v_fmac_f32_e32 v4, v5, v5
	v_fmac_f32_e32 v4, v42, v42
	v_lshlrev_b32_e32 v5, 16, v43
	v_and_b32_e32 v43, 0xffff0000, v43
	v_fmac_f32_e32 v4, v5, v5
	v_fmac_f32_e32 v4, v43, v43
	v_lshlrev_b32_e32 v5, 16, v44
	v_and_b32_e32 v44, 0xffff0000, v44
	v_fmac_f32_e32 v4, v5, v5
	v_fmac_f32_e32 v4, v44, v44
	v_lshlrev_b32_e32 v5, 16, v45
	v_and_b32_e32 v45, 0xffff0000, v45
	v_fmac_f32_e32 v4, v5, v5
	v_fmac_f32_e32 v4, v45, v45
	s_waitcnt vmcnt(21)
	v_lshlrev_b32_e32 v5, 16, v46
	v_and_b32_e32 v46, 0xffff0000, v46
	v_fmac_f32_e32 v4, v5, v5
	v_fmac_f32_e32 v4, v46, v46
	v_lshlrev_b32_e32 v5, 16, v47
	v_and_b32_e32 v47, 0xffff0000, v47
	v_fmac_f32_e32 v4, v5, v5
	v_fmac_f32_e32 v4, v47, v47
	v_lshlrev_b32_e32 v5, 16, v48
	v_and_b32_e32 v48, 0xffff0000, v48
	v_fmac_f32_e32 v4, v5, v5
	v_fmac_f32_e32 v4, v48, v48
	v_lshlrev_b32_e32 v5, 16, v49
	v_and_b32_e32 v49, 0xffff0000, v49
	v_fmac_f32_e32 v4, v5, v5
	v_fmac_f32_e32 v4, v49, v49
	s_waitcnt vmcnt(20)
	v_lshlrev_b32_e32 v5, 16, v50
	v_and_b32_e32 v50, 0xffff0000, v50
	v_fmac_f32_e32 v4, v5, v5
	v_fmac_f32_e32 v4, v50, v50
	v_lshlrev_b32_e32 v5, 16, v51
	v_and_b32_e32 v51, 0xffff0000, v51
	v_fmac_f32_e32 v4, v5, v5
	v_fmac_f32_e32 v4, v51, v51
	v_lshlrev_b32_e32 v5, 16, v52
	v_and_b32_e32 v52, 0xffff0000, v52
	v_fmac_f32_e32 v4, v5, v5
	v_fmac_f32_e32 v4, v52, v52
	v_lshlrev_b32_e32 v5, 16, v53
	v_and_b32_e32 v53, 0xffff0000, v53
	v_fmac_f32_e32 v4, v5, v5
	v_fmac_f32_e32 v4, v53, v53
	s_waitcnt vmcnt(19)
	v_lshlrev_b32_e32 v5, 16, v54
	v_and_b32_e32 v54, 0xffff0000, v54
	v_fmac_f32_e32 v4, v5, v5
	v_fmac_f32_e32 v4, v54, v54
	v_lshlrev_b32_e32 v5, 16, v55
	v_and_b32_e32 v55, 0xffff0000, v55
	v_fmac_f32_e32 v4, v5, v5
	v_fmac_f32_e32 v4, v55, v55
	v_lshlrev_b32_e32 v5, 16, v56
	v_and_b32_e32 v56, 0xffff0000, v56
	v_fmac_f32_e32 v4, v5, v5
	v_fmac_f32_e32 v4, v56, v56
	v_lshlrev_b32_e32 v5, 16, v57
	v_and_b32_e32 v57, 0xffff0000, v57
	v_fmac_f32_e32 v4, v5, v5
	v_fmac_f32_e32 v4, v57, v57
	s_waitcnt vmcnt(18)
	v_lshlrev_b32_e32 v5, 16, v58
	v_and_b32_e32 v58, 0xffff0000, v58
	v_fmac_f32_e32 v4, v5, v5
	v_fmac_f32_e32 v4, v58, v58
	v_lshlrev_b32_e32 v5, 16, v59
	v_and_b32_e32 v59, 0xffff0000, v59
	v_fmac_f32_e32 v4, v5, v5
	v_fmac_f32_e32 v4, v59, v59
	v_lshlrev_b32_e32 v5, 16, v60
	v_and_b32_e32 v60, 0xffff0000, v60
	v_fmac_f32_e32 v4, v5, v5
	v_fmac_f32_e32 v4, v60, v60
	v_lshlrev_b32_e32 v5, 16, v61
	v_and_b32_e32 v61, 0xffff0000, v61
	v_fmac_f32_e32 v4, v5, v5
	v_fmac_f32_e32 v4, v61, v61
	s_waitcnt vmcnt(17)
	v_lshlrev_b32_e32 v5, 16, v62
	v_and_b32_e32 v62, 0xffff0000, v62
	v_fmac_f32_e32 v4, v5, v5
	v_fmac_f32_e32 v4, v62, v62
	v_lshlrev_b32_e32 v5, 16, v63
	v_and_b32_e32 v63, 0xffff0000, v63
	v_fmac_f32_e32 v4, v5, v5
	v_fmac_f32_e32 v4, v63, v63
	v_lshlrev_b32_e32 v5, 16, v64
	v_and_b32_e32 v64, 0xffff0000, v64
	v_fmac_f32_e32 v4, v5, v5
	v_fmac_f32_e32 v4, v64, v64
	v_lshlrev_b32_e32 v5, 16, v65
	v_and_b32_e32 v65, 0xffff0000, v65
	v_fmac_f32_e32 v4, v5, v5
	v_fmac_f32_e32 v4, v65, v65
	s_waitcnt vmcnt(16)
	v_lshlrev_b32_e32 v5, 16, v66
	v_and_b32_e32 v66, 0xffff0000, v66
	v_fmac_f32_e32 v4, v5, v5
	v_fmac_f32_e32 v4, v66, v66
	v_lshlrev_b32_e32 v5, 16, v67
	v_and_b32_e32 v67, 0xffff0000, v67
	v_fmac_f32_e32 v4, v5, v5
	v_fmac_f32_e32 v4, v67, v67
	v_lshlrev_b32_e32 v5, 16, v68
	v_and_b32_e32 v68, 0xffff0000, v68
	v_fmac_f32_e32 v4, v5, v5
	v_fmac_f32_e32 v4, v68, v68
	v_lshlrev_b32_e32 v5, 16, v69
	v_and_b32_e32 v69, 0xffff0000, v69
	v_fmac_f32_e32 v4, v5, v5
	v_fmac_f32_e32 v4, v69, v69
	s_waitcnt vmcnt(15)
	v_lshlrev_b32_e32 v5, 16, v70
	v_and_b32_e32 v70, 0xffff0000, v70
	v_fmac_f32_e32 v4, v5, v5
	v_fmac_f32_e32 v4, v70, v70
	v_lshlrev_b32_e32 v5, 16, v71
	v_and_b32_e32 v71, 0xffff0000, v71
	v_fmac_f32_e32 v4, v5, v5
	v_fmac_f32_e32 v4, v71, v71
	v_lshlrev_b32_e32 v5, 16, v72
	v_and_b32_e32 v72, 0xffff0000, v72
	v_fmac_f32_e32 v4, v5, v5
	v_fmac_f32_e32 v4, v72, v72
	v_lshlrev_b32_e32 v5, 16, v73
	v_and_b32_e32 v73, 0xffff0000, v73
	v_fmac_f32_e32 v4, v5, v5
	v_fmac_f32_e32 v4, v73, v73
	s_waitcnt vmcnt(14)
	v_lshlrev_b32_e32 v5, 16, v74
	v_and_b32_e32 v74, 0xffff0000, v74
	v_fmac_f32_e32 v4, v5, v5
	v_fmac_f32_e32 v4, v74, v74
	v_lshlrev_b32_e32 v5, 16, v75
	v_and_b32_e32 v75, 0xffff0000, v75
	v_fmac_f32_e32 v4, v5, v5
	v_fmac_f32_e32 v4, v75, v75
	v_lshlrev_b32_e32 v5, 16, v76
	v_and_b32_e32 v76, 0xffff0000, v76
	v_fmac_f32_e32 v4, v5, v5
	v_fmac_f32_e32 v4, v76, v76
	v_lshlrev_b32_e32 v5, 16, v77
	v_and_b32_e32 v77, 0xffff0000, v77
	v_fmac_f32_e32 v4, v5, v5
	v_fmac_f32_e32 v4, v77, v77
	s_waitcnt vmcnt(13)
	v_lshlrev_b32_e32 v5, 16, v78
	v_and_b32_e32 v78, 0xffff0000, v78
	v_fmac_f32_e32 v4, v5, v5
	v_fmac_f32_e32 v4, v78, v78
	v_lshlrev_b32_e32 v5, 16, v79
	v_and_b32_e32 v79, 0xffff0000, v79
	v_fmac_f32_e32 v4, v5, v5
	v_fmac_f32_e32 v4, v79, v79
	v_lshlrev_b32_e32 v5, 16, v80
	v_and_b32_e32 v80, 0xffff0000, v80
	v_fmac_f32_e32 v4, v5, v5
	v_fmac_f32_e32 v4, v80, v80
	v_lshlrev_b32_e32 v5, 16, v81
	v_and_b32_e32 v81, 0xffff0000, v81
	v_fmac_f32_e32 v4, v5, v5
	v_fmac_f32_e32 v4, v81, v81
	s_waitcnt vmcnt(12)
; DI float bf2f(unsigned short b) { return __uint_as_float(((unsigned)b) << 16); }
; DI int tidx() { int t = threadIdx.x; asm volatile("" : "+v"(t)); return t; }
; template <int W>
; DI void row_rms(const bf16_t* src, int row0, float* rs) {
;     const int tid = tidx(), r = tid >> 1, hf = tid & 1;
;     const bf16_t* q = src + (size_t)(row0 + r) * W + hf * (W / 2);
;     float ss = 0.f;
; #pragma unroll 4
;     for (int i = 0; i < W / 16; ++i) {
;         const bf16x8 v = *(const bf16x8*)(q + i * 8);
; #pragma unroll
;         for (int e = 0; e < 8; ++e) { const float f = bf2f((unsigned short)v[e]); ss += f * f; }
;     }
;     ss += __shfl_xor(ss, 1);
;     if (hf == 0) rs[r] = rsqrtf(ss * (1.f / W) + 1e-6f);
;     __syncthreads();
; }
	v_lshlrev_b32_e32 v5, 16, v82
	v_and_b32_e32 v82, 0xffff0000, v82
	v_fmac_f32_e32 v4, v5, v5
	v_fmac_f32_e32 v4, v82, v82
	v_lshlrev_b32_e32 v5, 16, v83
	v_and_b32_e32 v83, 0xffff0000, v83
	v_fmac_f32_e32 v4, v5, v5
	v_fmac_f32_e32 v4, v83, v83
	v_lshlrev_b32_e32 v5, 16, v84
	v_and_b32_e32 v84, 0xffff0000, v84
	v_fmac_f32_e32 v4, v5, v5
	v_fmac_f32_e32 v4, v84, v84
	v_lshlrev_b32_e32 v5, 16, v85
	v_and_b32_e32 v85, 0xffff0000, v85
	v_fmac_f32_e32 v4, v5, v5
	v_fmac_f32_e32 v4, v85, v85
	s_waitcnt vmcnt(11)
	v_lshlrev_b32_e32 v5, 16, v86
	v_and_b32_e32 v86, 0xffff0000, v86
	v_fmac_f32_e32 v4, v5, v5
	v_fmac_f32_e32 v4, v86, v86
	v_lshlrev_b32_e32 v5, 16, v87
	v_and_b32_e32 v87, 0xffff0000, v87
	v_fmac_f32_e32 v4, v5, v5
	v_fmac_f32_e32 v4, v87, v87
	v_lshlrev_b32_e32 v5, 16, v88
	v_and_b32_e32 v88, 0xffff0000, v88
	v_fmac_f32_e32 v4, v5, v5
	v_fmac_f32_e32 v4, v88, v88
	v_lshlrev_b32_e32 v5, 16, v89
	v_and_b32_e32 v89, 0xffff0000, v89
	v_fmac_f32_e32 v4, v5, v5
	v_fmac_f32_e32 v4, v89, v89
	s_waitcnt vmcnt(10)
	v_lshlrev_b32_e32 v5, 16, v90
	v_and_b32_e32 v90, 0xffff0000, v90
	v_fmac_f32_e32 v4, v5, v5
	v_fmac_f32_e32 v4, v90, v90
	v_lshlrev_b32_e32 v5, 16, v91
	v_and_b32_e32 v91, 0xffff0000, v91
	v_fmac_f32_e32 v4, v5, v5
	v_fmac_f32_e32 v4, v91, v91
	v_lshlrev_b32_e32 v5, 16, v92
	v_and_b32_e32 v92, 0xffff0000, v92
	v_fmac_f32_e32 v4, v5, v5
	v_fmac_f32_e32 v4, v92, v92
	v_lshlrev_b32_e32 v5, 16, v93
	v_and_b32_e32 v93, 0xffff0000, v93
	v_fmac_f32_e32 v4, v5, v5
	v_fmac_f32_e32 v4, v93, v93
	s_waitcnt vmcnt(9)
	v_lshlrev_b32_e32 v5, 16, v94
	v_and_b32_e32 v94, 0xffff0000, v94
	v_fmac_f32_e32 v4, v5, v5
	v_fmac_f32_e32 v4, v94, v94
	v_lshlrev_b32_e32 v5, 16, v95
	v_and_b32_e32 v95, 0xffff0000, v95
	v_fmac_f32_e32 v4, v5, v5
	v_fmac_f32_e32 v4, v95, v95
	v_lshlrev_b32_e32 v5, 16, v96
	v_and_b32_e32 v96, 0xffff0000, v96
	v_fmac_f32_e32 v4, v5, v5
	v_fmac_f32_e32 v4, v96, v96
	v_lshlrev_b32_e32 v5, 16, v97
	v_and_b32_e32 v97, 0xffff0000, v97
	v_fmac_f32_e32 v4, v5, v5
	v_fmac_f32_e32 v4, v97, v97
	s_waitcnt vmcnt(8)
	v_lshlrev_b32_e32 v5, 16, v98
	v_and_b32_e32 v98, 0xffff0000, v98
	v_fmac_f32_e32 v4, v5, v5
	v_fmac_f32_e32 v4, v98, v98
	v_lshlrev_b32_e32 v5, 16, v99
	v_and_b32_e32 v99, 0xffff0000, v99
	v_fmac_f32_e32 v4, v5, v5
	v_fmac_f32_e32 v4, v99, v99
	v_lshlrev_b32_e32 v5, 16, v100
	v_and_b32_e32 v100, 0xffff0000, v100
	v_fmac_f32_e32 v4, v5, v5
	v_fmac_f32_e32 v4, v100, v100
	v_lshlrev_b32_e32 v5, 16, v101
	v_and_b32_e32 v101, 0xffff0000, v101
	v_fmac_f32_e32 v4, v5, v5
	v_fmac_f32_e32 v4, v101, v101
	s_waitcnt vmcnt(7)
	v_lshlrev_b32_e32 v5, 16, v102
	v_and_b32_e32 v102, 0xffff0000, v102
	v_fmac_f32_e32 v4, v5, v5
	v_fmac_f32_e32 v4, v102, v102
	v_lshlrev_b32_e32 v5, 16, v103
	v_and_b32_e32 v103, 0xffff0000, v103
	v_fmac_f32_e32 v4, v5, v5
	v_fmac_f32_e32 v4, v103, v103
	v_lshlrev_b32_e32 v5, 16, v104
	v_and_b32_e32 v104, 0xffff0000, v104
	v_fmac_f32_e32 v4, v5, v5
	v_fmac_f32_e32 v4, v104, v104
	v_lshlrev_b32_e32 v5, 16, v105
	v_and_b32_e32 v105, 0xffff0000, v105
	v_fmac_f32_e32 v4, v5, v5
	v_fmac_f32_e32 v4, v105, v105
	s_waitcnt vmcnt(6)
	v_lshlrev_b32_e32 v5, 16, v106
	v_and_b32_e32 v106, 0xffff0000, v106
	v_fmac_f32_e32 v4, v5, v5
	v_fmac_f32_e32 v4, v106, v106
	v_lshlrev_b32_e32 v5, 16, v107
	v_and_b32_e32 v107, 0xffff0000, v107
	v_fmac_f32_e32 v4, v5, v5
	v_fmac_f32_e32 v4, v107, v107
	v_lshlrev_b32_e32 v5, 16, v108
	v_and_b32_e32 v108, 0xffff0000, v108
	v_fmac_f32_e32 v4, v5, v5
	v_fmac_f32_e32 v4, v108, v108
	v_lshlrev_b32_e32 v5, 16, v109
	v_and_b32_e32 v109, 0xffff0000, v109
	v_fmac_f32_e32 v4, v5, v5
	v_fmac_f32_e32 v4, v109, v109
	s_waitcnt vmcnt(5)
; DI float bf2f(unsigned short b) { return __uint_as_float(((unsigned)b) << 16); }
; DI int tidx() { int t = threadIdx.x; asm volatile("" : "+v"(t)); return t; }
; template <int W>
; DI void row_rms(const bf16_t* src, int row0, float* rs) {
;     const int tid = tidx(), r = tid >> 1, hf = tid & 1;
;     const bf16_t* q = src + (size_t)(row0 + r) * W + hf * (W / 2);
;     float ss = 0.f;
; #pragma unroll 4
;     for (int i = 0; i < W / 16; ++i) {
;         const bf16x8 v = *(const bf16x8*)(q + i * 8);
; #pragma unroll
;         for (int e = 0; e < 8; ++e) { const float f = bf2f((unsigned short)v[e]); ss += f * f; }
;     }
;     ss += __shfl_xor(ss, 1);
;     if (hf == 0) rs[r] = rsqrtf(ss * (1.f / W) + 1e-6f);
;     __syncthreads();
; }
	v_lshlrev_b32_e32 v5, 16, v110
	v_and_b32_e32 v110, 0xffff0000, v110
	v_fmac_f32_e32 v4, v5, v5
	v_fmac_f32_e32 v4, v110, v110
	v_lshlrev_b32_e32 v5, 16, v111
	v_and_b32_e32 v111, 0xffff0000, v111
	v_fmac_f32_e32 v4, v5, v5
	v_fmac_f32_e32 v4, v111, v111
	v_lshlrev_b32_e32 v5, 16, v112
	v_and_b32_e32 v112, 0xffff0000, v112
	v_fmac_f32_e32 v4, v5, v5
	v_fmac_f32_e32 v4, v112, v112
	v_lshlrev_b32_e32 v5, 16, v113
	v_and_b32_e32 v113, 0xffff0000, v113
	v_fmac_f32_e32 v4, v5, v5
	v_fmac_f32_e32 v4, v113, v113
	s_waitcnt vmcnt(4)
	v_lshlrev_b32_e32 v5, 16, v114
	v_and_b32_e32 v114, 0xffff0000, v114
	v_fmac_f32_e32 v4, v5, v5
	v_fmac_f32_e32 v4, v114, v114
	v_lshlrev_b32_e32 v5, 16, v115
	v_and_b32_e32 v115, 0xffff0000, v115
	v_fmac_f32_e32 v4, v5, v5
	v_fmac_f32_e32 v4, v115, v115
	v_lshlrev_b32_e32 v5, 16, v116
	v_and_b32_e32 v116, 0xffff0000, v116
	v_fmac_f32_e32 v4, v5, v5
	v_fmac_f32_e32 v4, v116, v116
	v_lshlrev_b32_e32 v5, 16, v117
	v_and_b32_e32 v117, 0xffff0000, v117
	v_fmac_f32_e32 v4, v5, v5
	v_fmac_f32_e32 v4, v117, v117
	s_waitcnt vmcnt(3)
	v_lshlrev_b32_e32 v5, 16, v118
	v_and_b32_e32 v118, 0xffff0000, v118
	v_fmac_f32_e32 v4, v5, v5
	v_fmac_f32_e32 v4, v118, v118
	v_lshlrev_b32_e32 v5, 16, v119
	v_and_b32_e32 v119, 0xffff0000, v119
	v_fmac_f32_e32 v4, v5, v5
	v_fmac_f32_e32 v4, v119, v119
	v_lshlrev_b32_e32 v5, 16, v120
	v_and_b32_e32 v120, 0xffff0000, v120
	v_fmac_f32_e32 v4, v5, v5
	v_fmac_f32_e32 v4, v120, v120
	v_lshlrev_b32_e32 v5, 16, v121
	v_and_b32_e32 v121, 0xffff0000, v121
	v_fmac_f32_e32 v4, v5, v5
	v_fmac_f32_e32 v4, v121, v121
	s_waitcnt vmcnt(2)
	v_lshlrev_b32_e32 v5, 16, v122
	v_and_b32_e32 v122, 0xffff0000, v122
	v_fmac_f32_e32 v4, v5, v5
	v_fmac_f32_e32 v4, v122, v122
	v_lshlrev_b32_e32 v5, 16, v123
	v_and_b32_e32 v123, 0xffff0000, v123
	v_fmac_f32_e32 v4, v5, v5
	v_fmac_f32_e32 v4, v123, v123
	v_lshlrev_b32_e32 v5, 16, v124
	v_and_b32_e32 v124, 0xffff0000, v124
	v_fmac_f32_e32 v4, v5, v5
	v_fmac_f32_e32 v4, v124, v124
	v_lshlrev_b32_e32 v5, 16, v125
	v_and_b32_e32 v125, 0xffff0000, v125
	v_fmac_f32_e32 v4, v5, v5
	v_fmac_f32_e32 v4, v125, v125
	s_waitcnt vmcnt(1)
	v_lshlrev_b32_e32 v5, 16, v126
	v_and_b32_e32 v126, 0xffff0000, v126
	v_fmac_f32_e32 v4, v5, v5
	v_fmac_f32_e32 v4, v126, v126
	v_lshlrev_b32_e32 v5, 16, v127
	v_and_b32_e32 v127, 0xffff0000, v127
	v_fmac_f32_e32 v4, v5, v5
	v_fmac_f32_e32 v4, v127, v127
	v_lshlrev_b32_e32 v5, 16, v128
	v_and_b32_e32 v128, 0xffff0000, v128
	v_fmac_f32_e32 v4, v5, v5
	v_fmac_f32_e32 v4, v128, v128
	v_lshlrev_b32_e32 v5, 16, v129
	v_and_b32_e32 v129, 0xffff0000, v129
	v_fmac_f32_e32 v4, v5, v5
	v_fmac_f32_e32 v4, v129, v129
	s_waitcnt vmcnt(0)
	v_lshlrev_b32_e32 v5, 16, v130
	v_and_b32_e32 v130, 0xffff0000, v130
	v_fmac_f32_e32 v4, v5, v5
	v_fmac_f32_e32 v4, v130, v130
	v_lshlrev_b32_e32 v5, 16, v131
	v_and_b32_e32 v131, 0xffff0000, v131
	v_fmac_f32_e32 v4, v5, v5
	v_fmac_f32_e32 v4, v131, v131
	v_lshlrev_b32_e32 v5, 16, v132
	v_and_b32_e32 v132, 0xffff0000, v132
	v_fmac_f32_e32 v4, v5, v5
	v_fmac_f32_e32 v4, v132, v132
	v_lshlrev_b32_e32 v5, 16, v133
	v_and_b32_e32 v133, 0xffff0000, v133
	v_fmac_f32_e32 v4, v5, v5
	v_fmac_f32_e32 v4, v133, v133
	v_and_b32_e32 v1, 64, v157
	v_xor_b32_e32 v0, 1, v157
	v_add_u32_e32 v1, 64, v1
	v_cmp_lt_i32_e32 vcc, v0, v1
	s_nop 1
	v_cndmask_b32_e32 v0, v157, v0, vcc
	v_lshlrev_b32_e32 v0, 2, v0
	ds_bpermute_b32 v0, v0, v4
	v_cmp_eq_u32_e32 vcc, 0, v3
	s_and_saveexec_b64 s[54:55], vcc
	s_cbranch_execz .LBB0_919
	s_waitcnt lgkmcnt(0)
	v_add_f32_e32 v0, v4, v0
	v_fmamk_f32 v0, v0, 0x3b000000, v156
	s_mov_b32 s6, 0x800000
	v_mul_f32_e32 v1, 0x4b800000, v0
	v_cmp_gt_f32_e32 vcc, s6, v0
	s_nop 1
	v_cndmask_b32_e32 v0, v0, v1, vcc
	v_rsq_f32_e32 v0, v0
	v_lshl_add_u32 v1, v2, 2, 16
	v_add_u32_e32 v1, 0x20000, v1
	v_mul_f32_e32 v2, 0x45800000, v0
	v_cndmask_b32_e32 v0, v0, v2, vcc
	ds_write_b32 v1, v0

; DI float bf2f(unsigned short b) { return __uint_as_float(((unsigned)b) << 16); }
; DI int tidx() { int t = threadIdx.x; asm volatile("" : "+v"(t)); return t; }
; template <int W>
; DI void row_rms(const bf16_t* src, int row0, float* rs) {
;     const int tid = tidx(), r = tid >> 1, hf = tid & 1;
;     const bf16_t* q = src + (size_t)(row0 + r) * W + hf * (W / 2);
;     float ss = 0.f;
; #pragma unroll 4
;     for (int i = 0; i < W / 16; ++i) {
;         const bf16x8 v = *(const bf16x8*)(q + i * 8);
; #pragma unroll
;         for (int e = 0; e < 8; ++e) { const float f = bf2f((unsigned short)v[e]); ss += f * f; }
;     }
;     ss += __shfl_xor(ss, 1);
;     if (hf == 0) rs[r] = rsqrtf(ss * (1.f / W) + 1e-6f);
;     __syncthreads();
; }
.LBB0_922:
	global_load_dwordx4 v[6:9], v[0:1], off offset:-32
	global_load_dwordx4 v[10:13], v[0:1], off offset:-16
	global_load_dwordx4 v[14:17], v[0:1], off offset:0
	global_load_dwordx4 v[18:21], v[0:1], off offset:16
	global_load_dwordx4 v[22:25], v[0:1], off offset:32
	global_load_dwordx4 v[26:29], v[0:1], off offset:48
	global_load_dwordx4 v[30:33], v[0:1], off offset:64
	global_load_dwordx4 v[34:37], v[0:1], off offset:80
	global_load_dwordx4 v[38:41], v[0:1], off offset:96
	global_load_dwordx4 v[42:45], v[0:1], off offset:112
	global_load_dwordx4 v[46:49], v[0:1], off offset:128
	global_load_dwordx4 v[50:53], v[0:1], off offset:144
	global_load_dwordx4 v[54:57], v[0:1], off offset:160
	global_load_dwordx4 v[58:61], v[0:1], off offset:176
	global_load_dwordx4 v[62:65], v[0:1], off offset:192
	global_load_dwordx4 v[66:69], v[0:1], off offset:208
	s_waitcnt vmcnt(15)
	v_lshlrev_b32_e32 v5, 16, v6
	v_and_b32_e32 v6, 0xffff0000, v6
	v_fmac_f32_e32 v4, v5, v5
	v_fmac_f32_e32 v4, v6, v6
	v_lshlrev_b32_e32 v5, 16, v7
	v_and_b32_e32 v7, 0xffff0000, v7
	v_fmac_f32_e32 v4, v5, v5
	v_fmac_f32_e32 v4, v7, v7
	v_lshlrev_b32_e32 v5, 16, v8
	v_and_b32_e32 v8, 0xffff0000, v8
	v_fmac_f32_e32 v4, v5, v5
	v_fmac_f32_e32 v4, v8, v8
	v_lshlrev_b32_e32 v5, 16, v9
	v_and_b32_e32 v9, 0xffff0000, v9
	v_fmac_f32_e32 v4, v5, v5
	v_fmac_f32_e32 v4, v9, v9
	s_waitcnt vmcnt(14)
	v_lshlrev_b32_e32 v5, 16, v10
	v_and_b32_e32 v10, 0xffff0000, v10
	v_fmac_f32_e32 v4, v5, v5
	v_fmac_f32_e32 v4, v10, v10
	v_lshlrev_b32_e32 v5, 16, v11
	v_and_b32_e32 v11, 0xffff0000, v11
	v_fmac_f32_e32 v4, v5, v5
	v_fmac_f32_e32 v4, v11, v11
	v_lshlrev_b32_e32 v5, 16, v12
	v_and_b32_e32 v12, 0xffff0000, v12
	v_fmac_f32_e32 v4, v5, v5
	v_fmac_f32_e32 v4, v12, v12
	v_lshlrev_b32_e32 v5, 16, v13
	v_and_b32_e32 v13, 0xffff0000, v13
	v_fmac_f32_e32 v4, v5, v5
	v_fmac_f32_e32 v4, v13, v13
	s_waitcnt vmcnt(13)
	v_lshlrev_b32_e32 v5, 16, v14
	v_and_b32_e32 v14, 0xffff0000, v14
	v_fmac_f32_e32 v4, v5, v5
	v_fmac_f32_e32 v4, v14, v14
	v_lshlrev_b32_e32 v5, 16, v15
	v_and_b32_e32 v15, 0xffff0000, v15
	v_fmac_f32_e32 v4, v5, v5
	v_fmac_f32_e32 v4, v15, v15
	v_lshlrev_b32_e32 v5, 16, v16
	v_and_b32_e32 v16, 0xffff0000, v16
	v_fmac_f32_e32 v4, v5, v5
	v_fmac_f32_e32 v4, v16, v16
	v_lshlrev_b32_e32 v5, 16, v17
	v_and_b32_e32 v17, 0xffff0000, v17
	v_fmac_f32_e32 v4, v5, v5
	v_fmac_f32_e32 v4, v17, v17
	s_waitcnt vmcnt(12)
	v_lshlrev_b32_e32 v5, 16, v18
	v_and_b32_e32 v18, 0xffff0000, v18
	v_fmac_f32_e32 v4, v5, v5
	v_fmac_f32_e32 v4, v18, v18
	v_lshlrev_b32_e32 v5, 16, v19
	v_and_b32_e32 v19, 0xffff0000, v19
	v_fmac_f32_e32 v4, v5, v5
	v_fmac_f32_e32 v4, v19, v19
	v_lshlrev_b32_e32 v5, 16, v20
	v_and_b32_e32 v20, 0xffff0000, v20
	v_fmac_f32_e32 v4, v5, v5
	v_fmac_f32_e32 v4, v20, v20
	v_lshlrev_b32_e32 v5, 16, v21
	v_and_b32_e32 v21, 0xffff0000, v21
	v_fmac_f32_e32 v4, v5, v5
	v_fmac_f32_e32 v4, v21, v21
	s_waitcnt vmcnt(11)
	v_lshlrev_b32_e32 v5, 16, v22
	v_and_b32_e32 v22, 0xffff0000, v22
	v_fmac_f32_e32 v4, v5, v5
	v_fmac_f32_e32 v4, v22, v22
	v_lshlrev_b32_e32 v5, 16, v23
	v_and_b32_e32 v23, 0xffff0000, v23
	v_fmac_f32_e32 v4, v5, v5
	v_fmac_f32_e32 v4, v23, v23
	v_lshlrev_b32_e32 v5, 16, v24
	v_and_b32_e32 v24, 0xffff0000, v24
	v_fmac_f32_e32 v4, v5, v5
	v_fmac_f32_e32 v4, v24, v24
	v_lshlrev_b32_e32 v5, 16, v25
	v_and_b32_e32 v25, 0xffff0000, v25
	v_fmac_f32_e32 v4, v5, v5
	v_fmac_f32_e32 v4, v25, v25
	s_waitcnt vmcnt(10)
	v_lshlrev_b32_e32 v5, 16, v26
	v_and_b32_e32 v26, 0xffff0000, v26
	v_fmac_f32_e32 v4, v5, v5
	v_fmac_f32_e32 v4, v26, v26
	v_lshlrev_b32_e32 v5, 16, v27
	v_and_b32_e32 v27, 0xffff0000, v27
	v_fmac_f32_e32 v4, v5, v5
	v_fmac_f32_e32 v4, v27, v27
	v_lshlrev_b32_e32 v5, 16, v28
	v_and_b32_e32 v28, 0xffff0000, v28
	v_fmac_f32_e32 v4, v5, v5
	v_fmac_f32_e32 v4, v28, v28
	v_lshlrev_b32_e32 v5, 16, v29
	v_and_b32_e32 v29, 0xffff0000, v29
	v_fmac_f32_e32 v4, v5, v5
	v_fmac_f32_e32 v4, v29, v29
	s_waitcnt vmcnt(9)
	v_lshlrev_b32_e32 v5, 16, v30
	v_and_b32_e32 v30, 0xffff0000, v30
	v_fmac_f32_e32 v4, v5, v5
	v_fmac_f32_e32 v4, v30, v30
	v_lshlrev_b32_e32 v5, 16, v31
	v_and_b32_e32 v31, 0xffff0000, v31
	v_fmac_f32_e32 v4, v5, v5
	v_fmac_f32_e32 v4, v31, v31
	v_lshlrev_b32_e32 v5, 16, v32
	v_and_b32_e32 v32, 0xffff0000, v32
	v_fmac_f32_e32 v4, v5, v5
	v_fmac_f32_e32 v4, v32, v32
	v_lshlrev_b32_e32 v5, 16, v33
	v_and_b32_e32 v33, 0xffff0000, v33
	v_fmac_f32_e32 v4, v5, v5
	v_fmac_f32_e32 v4, v33, v33
	s_waitcnt vmcnt(8)
	v_lshlrev_b32_e32 v5, 16, v34
	v_and_b32_e32 v34, 0xffff0000, v34
	v_fmac_f32_e32 v4, v5, v5
	v_fmac_f32_e32 v4, v34, v34
	v_lshlrev_b32_e32 v5, 16, v35
	v_and_b32_e32 v35, 0xffff0000, v35
	v_fmac_f32_e32 v4, v5, v5
	v_fmac_f32_e32 v4, v35, v35
	v_lshlrev_b32_e32 v5, 16, v36
	v_and_b32_e32 v36, 0xffff0000, v36
	v_fmac_f32_e32 v4, v5, v5
	v_fmac_f32_e32 v4, v36, v36
	v_lshlrev_b32_e32 v5, 16, v37
	v_and_b32_e32 v37, 0xffff0000, v37
	v_fmac_f32_e32 v4, v5, v5
	v_fmac_f32_e32 v4, v37, v37
	s_waitcnt vmcnt(7)
; DI float bf2f(unsigned short b) { return __uint_as_float(((unsigned)b) << 16); }
; DI int tidx() { int t = threadIdx.x; asm volatile("" : "+v"(t)); return t; }
; template <int W>
; DI void row_rms(const bf16_t* src, int row0, float* rs) {
;     const int tid = tidx(), r = tid >> 1, hf = tid & 1;
;     const bf16_t* q = src + (size_t)(row0 + r) * W + hf * (W / 2);
;     float ss = 0.f;
; #pragma unroll 4
;     for (int i = 0; i < W / 16; ++i) {
;         const bf16x8 v = *(const bf16x8*)(q + i * 8);
; #pragma unroll
;         for (int e = 0; e < 8; ++e) { const float f = bf2f((unsigned short)v[e]); ss += f * f; }
;     }
;     ss += __shfl_xor(ss, 1);
;     if (hf == 0) rs[r] = rsqrtf(ss * (1.f / W) + 1e-6f);
;     __syncthreads();
; }
	v_lshlrev_b32_e32 v5, 16, v38
	v_and_b32_e32 v38, 0xffff0000, v38
	v_fmac_f32_e32 v4, v5, v5
	v_fmac_f32_e32 v4, v38, v38
	v_lshlrev_b32_e32 v5, 16, v39
	v_and_b32_e32 v39, 0xffff0000, v39
	v_fmac_f32_e32 v4, v5, v5
	v_fmac_f32_e32 v4, v39, v39
	v_lshlrev_b32_e32 v5, 16, v40
	v_and_b32_e32 v40, 0xffff0000, v40
	v_fmac_f32_e32 v4, v5, v5
	v_fmac_f32_e32 v4, v40, v40
	v_lshlrev_b32_e32 v5, 16, v41
	v_and_b32_e32 v41, 0xffff0000, v41
	v_fmac_f32_e32 v4, v5, v5
	v_fmac_f32_e32 v4, v41, v41
	s_waitcnt vmcnt(6)
	v_lshlrev_b32_e32 v5, 16, v42
	v_and_b32_e32 v42, 0xffff0000, v42
	v_fmac_f32_e32 v4, v5, v5
	v_fmac_f32_e32 v4, v42, v42
	v_lshlrev_b32_e32 v5, 16, v43
	v_and_b32_e32 v43, 0xffff0000, v43
	v_fmac_f32_e32 v4, v5, v5
	v_fmac_f32_e32 v4, v43, v43
	v_lshlrev_b32_e32 v5, 16, v44
	v_and_b32_e32 v44, 0xffff0000, v44
	v_fmac_f32_e32 v4, v5, v5
	v_fmac_f32_e32 v4, v44, v44
	v_lshlrev_b32_e32 v5, 16, v45
	v_and_b32_e32 v45, 0xffff0000, v45
	v_fmac_f32_e32 v4, v5, v5
	v_fmac_f32_e32 v4, v45, v45
	s_waitcnt vmcnt(5)
	v_lshlrev_b32_e32 v5, 16, v46
	v_and_b32_e32 v46, 0xffff0000, v46
	v_fmac_f32_e32 v4, v5, v5
	v_fmac_f32_e32 v4, v46, v46
	v_lshlrev_b32_e32 v5, 16, v47
	v_and_b32_e32 v47, 0xffff0000, v47
	v_fmac_f32_e32 v4, v5, v5
	v_fmac_f32_e32 v4, v47, v47
	v_lshlrev_b32_e32 v5, 16, v48
	v_and_b32_e32 v48, 0xffff0000, v48
	v_fmac_f32_e32 v4, v5, v5
	v_fmac_f32_e32 v4, v48, v48
	v_lshlrev_b32_e32 v5, 16, v49
	v_and_b32_e32 v49, 0xffff0000, v49
	v_fmac_f32_e32 v4, v5, v5
	v_fmac_f32_e32 v4, v49, v49
	s_waitcnt vmcnt(4)
	v_lshlrev_b32_e32 v5, 16, v50
	v_and_b32_e32 v50, 0xffff0000, v50
	v_fmac_f32_e32 v4, v5, v5
	v_fmac_f32_e32 v4, v50, v50
	v_lshlrev_b32_e32 v5, 16, v51
	v_and_b32_e32 v51, 0xffff0000, v51
	v_fmac_f32_e32 v4, v5, v5
	v_fmac_f32_e32 v4, v51, v51
	v_lshlrev_b32_e32 v5, 16, v52
	v_and_b32_e32 v52, 0xffff0000, v52
	v_fmac_f32_e32 v4, v5, v5
	v_fmac_f32_e32 v4, v52, v52
	v_lshlrev_b32_e32 v5, 16, v53
	v_and_b32_e32 v53, 0xffff0000, v53
	v_fmac_f32_e32 v4, v5, v5
	v_fmac_f32_e32 v4, v53, v53
	s_waitcnt vmcnt(3)
	v_lshlrev_b32_e32 v5, 16, v54
	v_and_b32_e32 v54, 0xffff0000, v54
	v_fmac_f32_e32 v4, v5, v5
	v_fmac_f32_e32 v4, v54, v54
	v_lshlrev_b32_e32 v5, 16, v55
	v_and_b32_e32 v55, 0xffff0000, v55
	v_fmac_f32_e32 v4, v5, v5
	v_fmac_f32_e32 v4, v55, v55
	v_lshlrev_b32_e32 v5, 16, v56
	v_and_b32_e32 v56, 0xffff0000, v56
	v_fmac_f32_e32 v4, v5, v5
	v_fmac_f32_e32 v4, v56, v56
	v_lshlrev_b32_e32 v5, 16, v57
	v_and_b32_e32 v57, 0xffff0000, v57
	v_fmac_f32_e32 v4, v5, v5
	v_fmac_f32_e32 v4, v57, v57
	s_waitcnt vmcnt(2)
	v_lshlrev_b32_e32 v5, 16, v58
	v_and_b32_e32 v58, 0xffff0000, v58
	v_fmac_f32_e32 v4, v5, v5
	v_fmac_f32_e32 v4, v58, v58
	v_lshlrev_b32_e32 v5, 16, v59
	v_and_b32_e32 v59, 0xffff0000, v59
	v_fmac_f32_e32 v4, v5, v5
	v_fmac_f32_e32 v4, v59, v59
	v_lshlrev_b32_e32 v5, 16, v60
	v_and_b32_e32 v60, 0xffff0000, v60
	v_fmac_f32_e32 v4, v5, v5
	v_fmac_f32_e32 v4, v60, v60
	v_lshlrev_b32_e32 v5, 16, v61
	v_and_b32_e32 v61, 0xffff0000, v61
	v_fmac_f32_e32 v4, v5, v5
	v_fmac_f32_e32 v4, v61, v61
	s_waitcnt vmcnt(1)
	v_lshlrev_b32_e32 v5, 16, v62
	v_and_b32_e32 v62, 0xffff0000, v62
	v_fmac_f32_e32 v4, v5, v5
	v_fmac_f32_e32 v4, v62, v62
	v_lshlrev_b32_e32 v5, 16, v63
	v_and_b32_e32 v63, 0xffff0000, v63
	v_fmac_f32_e32 v4, v5, v5
	v_fmac_f32_e32 v4, v63, v63
	v_lshlrev_b32_e32 v5, 16, v64
	v_and_b32_e32 v64, 0xffff0000, v64
	v_fmac_f32_e32 v4, v5, v5
	v_fmac_f32_e32 v4, v64, v64
	v_lshlrev_b32_e32 v5, 16, v65
	v_and_b32_e32 v65, 0xffff0000, v65
	v_fmac_f32_e32 v4, v5, v5
	v_fmac_f32_e32 v4, v65, v65
	s_waitcnt vmcnt(0)
	v_lshlrev_b32_e32 v5, 16, v66
	v_and_b32_e32 v66, 0xffff0000, v66
	v_fmac_f32_e32 v4, v5, v5
	v_fmac_f32_e32 v4, v66, v66
	v_lshlrev_b32_e32 v5, 16, v67
	v_and_b32_e32 v67, 0xffff0000, v67
	v_fmac_f32_e32 v4, v5, v5
	v_fmac_f32_e32 v4, v67, v67
	v_lshlrev_b32_e32 v5, 16, v68
	v_and_b32_e32 v68, 0xffff0000, v68
	v_fmac_f32_e32 v4, v5, v5
	v_fmac_f32_e32 v4, v68, v68
	v_lshlrev_b32_e32 v5, 16, v69
	v_and_b32_e32 v69, 0xffff0000, v69
	v_fmac_f32_e32 v4, v5, v5
	v_fmac_f32_e32 v4, v69, v69
	v_and_b32_e32 v1, 64, v157
	v_xor_b32_e32 v0, 1, v157
	v_add_u32_e32 v1, 64, v1
	v_cmp_lt_i32_e32 vcc, v0, v1
	s_nop 1
	v_cndmask_b32_e32 v0, v157, v0, vcc
	v_lshlrev_b32_e32 v0, 2, v0
	ds_bpermute_b32 v0, v0, v4
	v_cmp_eq_u32_e32 vcc, 0, v3
	s_and_saveexec_b64 s[54:55], vcc
	s_cbranch_execz .LBB0_925
	s_waitcnt lgkmcnt(0)
	v_add_f32_e32 v0, v4, v0
	v_fmamk_f32 v0, v0, 0x3b800000, v156
	s_mov_b32 s6, 0x800000
	v_mul_f32_e32 v1, 0x4b800000, v0
	v_cmp_gt_f32_e32 vcc, s6, v0
	s_nop 1
	v_cndmask_b32_e32 v0, v0, v1, vcc
	v_rsq_f32_e32 v0, v0
	v_lshl_add_u32 v1, v2, 2, 16
	v_add_u32_e32 v1, 0x20000, v1
	v_mul_f32_e32 v2, 0x45800000, v0
	v_cndmask_b32_e32 v0, v0, v2, vcc
	ds_write_b32 v1, v0
